# v37 + GLA stage-1b: ieb computed as exp2(-x) (one v_exp with neg modifier) instead of IEEE 1/exp2(x) division, 15 of 16 unrolled sites
# speedup vs baseline: 1.0121x; 1.0022x over previous
; DEVI void gla_seq(const Params& p, int l, int item, char* lds) {
;     ...
;     {
;       float run = 0.f;
; #pragma unroll
;       for (int ii = 0; ii < 16; ++ii) {
;         const float* gr_ = gas + (seg * 16 + ii) * 16;
;         float z = ba;
; #pragma unroll
;         for (int r = 0; r < 16; ++r) z += gr_[r] * w2[r];
;         const float ls = fminf(z, 0.f) - __logf(1.f + __expf(-fabsf(z)));
;         run += ls * (1.f / 16.f);
;         bcum[ii] = run;
;       }
;       segtot[seg * 128 + d] = run;
.LBB0_399:
	ds_read_b128 v[16:19], v127
	ds_read_b128 v[20:23], v127 offset:16
	ds_read_b128 v[24:27], v127 offset:32
	ds_read_b128 v[28:31], v127 offset:48
	s_mov_b32 s29, 0x3f317217
	s_waitcnt lgkmcnt(3)
	v_fma_f32 v16, v106, v16, v122
	v_fmac_f32_e32 v16, v107, v17
	v_fmac_f32_e32 v16, v108, v18
	v_fmac_f32_e32 v16, v109, v19
	s_waitcnt lgkmcnt(2)
	v_fmac_f32_e32 v16, v110, v20
	v_fmac_f32_e32 v16, v111, v21
	v_fmac_f32_e32 v16, v112, v22
	v_fmac_f32_e32 v16, v113, v23
	s_waitcnt lgkmcnt(1)
	v_fmac_f32_e32 v16, v114, v24
	v_fmac_f32_e32 v16, v115, v25
	v_fmac_f32_e32 v16, v116, v26
	v_fmac_f32_e32 v16, v117, v27
	s_waitcnt lgkmcnt(0)
	v_fmac_f32_e32 v16, v118, v28
	v_fmac_f32_e32 v16, v119, v29
	v_fmac_f32_e32 v16, v120, v30
	v_fmac_f32_e32 v16, v121, v31
	v_min_f32_e32 v17, 0, v16
	v_mul_f32_e64 v16, |v16|, s54
	v_exp_f32_e32 v16, v16
	s_mov_b32 s27, 0x7f800000
	v_add_f32_e32 v16, 1.0, v16
	v_cmp_gt_f32_e32 vcc, s59, v16
	s_nop 1
	v_cndmask_b32_e64 v18, 0, 32, vcc
	v_ldexp_f32 v16, v16, v18
	v_log_f32_e32 v16, v16
	s_nop 0
	v_mul_f32_e32 v18, 0x3f317217, v16
	v_fma_f32 v18, v16, s29, -v18
	v_fmac_f32_e32 v18, 0x3377d1cf, v16
	v_fmac_f32_e32 v18, 0x3f317217, v16
	v_cmp_lt_f32_e64 s[2:3], |v16|, s27
	s_nop 1
	v_cndmask_b32_e64 v16, v16, v18, s[2:3]
	v_cndmask_b32_e32 v18, 0, v214, vcc
	v_sub_f32_e32 v16, v16, v18
	v_sub_f32_e32 v16, v17, v16
	s_mov_b32 s2, 0x3d800000
	v_fma_f32 v20, v16, s2, 0
	ds_read_b128 v[16:19], v127 offset:64
	s_waitcnt lgkmcnt(0)
	v_fma_f32 v21, v106, v16, v122
	v_fmac_f32_e32 v21, v107, v17
	v_fmac_f32_e32 v21, v108, v18
	v_fmac_f32_e32 v21, v109, v19
	ds_read_b128 v[16:19], v127 offset:80
	s_waitcnt lgkmcnt(0)
	v_fmac_f32_e32 v21, v110, v16
	v_fmac_f32_e32 v21, v111, v17
	v_fmac_f32_e32 v21, v112, v18
	v_fmac_f32_e32 v21, v113, v19
	ds_read_b128 v[16:19], v127 offset:96
	s_waitcnt lgkmcnt(0)
	v_fmac_f32_e32 v21, v114, v16
	v_fmac_f32_e32 v21, v115, v17
	v_fmac_f32_e32 v21, v116, v18
	v_fmac_f32_e32 v21, v117, v19
	ds_read_b128 v[16:19], v127 offset:112
	s_waitcnt lgkmcnt(0)
	v_fmac_f32_e32 v21, v118, v16
	v_fmac_f32_e32 v21, v119, v17
	v_fmac_f32_e32 v21, v120, v18
	v_fmac_f32_e32 v21, v121, v19
	v_mul_f32_e64 v17, |v21|, s54
	v_exp_f32_e32 v17, v17
	v_min_f32_e32 v16, 0, v21
	v_add_f32_e32 v17, 1.0, v17
	v_cmp_gt_f32_e32 vcc, s59, v17
	s_nop 1
	v_cndmask_b32_e64 v18, 0, 32, vcc
	v_ldexp_f32 v17, v17, v18
	v_log_f32_e32 v17, v17
	s_nop 0
	v_mul_f32_e32 v18, 0x3f317217, v17
	v_fma_f32 v18, v17, s29, -v18
	v_fmac_f32_e32 v18, 0x3377d1cf, v17
	v_fmac_f32_e32 v18, 0x3f317217, v17
	v_cmp_lt_f32_e64 s[2:3], |v17|, s27
	s_nop 1
	v_cndmask_b32_e64 v17, v17, v18, s[2:3]
	v_cndmask_b32_e32 v18, 0, v214, vcc
	v_sub_f32_e32 v17, v17, v18
	v_sub_f32_e32 v16, v16, v17
	v_fmamk_f32 v21, v16, 0x3d800000, v20
	ds_read_b128 v[16:19], v127 offset:128
	s_waitcnt lgkmcnt(0)
	v_fma_f32 v22, v106, v16, v122
	v_fmac_f32_e32 v22, v107, v17
	v_fmac_f32_e32 v22, v108, v18
	v_fmac_f32_e32 v22, v109, v19
	ds_read_b128 v[16:19], v127 offset:144
	s_waitcnt lgkmcnt(0)
	v_fmac_f32_e32 v22, v110, v16
	v_fmac_f32_e32 v22, v111, v17
	v_fmac_f32_e32 v22, v112, v18
	v_fmac_f32_e32 v22, v113, v19
	ds_read_b128 v[16:19], v127 offset:160
	s_waitcnt lgkmcnt(0)
	v_fmac_f32_e32 v22, v114, v16
	v_fmac_f32_e32 v22, v115, v17
	v_fmac_f32_e32 v22, v116, v18
	v_fmac_f32_e32 v22, v117, v19
	ds_read_b128 v[16:19], v127 offset:176
	s_waitcnt lgkmcnt(0)
	v_fmac_f32_e32 v22, v118, v16
	v_fmac_f32_e32 v22, v119, v17
	v_fmac_f32_e32 v22, v120, v18
	v_fmac_f32_e32 v22, v121, v19
	v_mul_f32_e64 v17, |v22|, s54
	v_exp_f32_e32 v17, v17
	v_min_f32_e32 v16, 0, v22
	v_add_f32_e32 v17, 1.0, v17
	v_cmp_gt_f32_e32 vcc, s59, v17
	s_nop 1
	v_cndmask_b32_e64 v18, 0, 32, vcc
	v_ldexp_f32 v17, v17, v18
	v_log_f32_e32 v17, v17
	s_nop 0
	v_mul_f32_e32 v18, 0x3f317217, v17
	v_fma_f32 v18, v17, s29, -v18
	v_fmac_f32_e32 v18, 0x3377d1cf, v17
	v_fmac_f32_e32 v18, 0x3f317217, v17
	v_cmp_lt_f32_e64 s[2:3], |v17|, s27
	s_nop 1
	v_cndmask_b32_e64 v17, v17, v18, s[2:3]
	v_cndmask_b32_e32 v18, 0, v214, vcc
	v_sub_f32_e32 v17, v17, v18
	v_sub_f32_e32 v16, v16, v17
	v_fmamk_f32 v22, v16, 0x3d800000, v21
	ds_read_b128 v[16:19], v127 offset:192
	s_waitcnt lgkmcnt(0)
	v_fma_f32 v23, v106, v16, v122
	v_fmac_f32_e32 v23, v107, v17
	v_fmac_f32_e32 v23, v108, v18
	v_fmac_f32_e32 v23, v109, v19
	ds_read_b128 v[16:19], v127 offset:208
	s_waitcnt lgkmcnt(0)
	v_fmac_f32_e32 v23, v110, v16
	v_fmac_f32_e32 v23, v111, v17
	v_fmac_f32_e32 v23, v112, v18
	v_fmac_f32_e32 v23, v113, v19
	ds_read_b128 v[16:19], v127 offset:224
	s_waitcnt lgkmcnt(0)
	v_fmac_f32_e32 v23, v114, v16
	v_fmac_f32_e32 v23, v115, v17
	v_fmac_f32_e32 v23, v116, v18
	v_fmac_f32_e32 v23, v117, v19
	ds_read_b128 v[16:19], v127 offset:240
	s_waitcnt lgkmcnt(0)
	v_fmac_f32_e32 v23, v118, v16
	v_fmac_f32_e32 v23, v119, v17
	v_fmac_f32_e32 v23, v120, v18
	v_fmac_f32_e32 v23, v121, v19
	v_mul_f32_e64 v17, |v23|, s54
	v_exp_f32_e32 v17, v17
	v_min_f32_e32 v16, 0, v23
	v_add_f32_e32 v17, 1.0, v17
	v_cmp_gt_f32_e32 vcc, s59, v17
	s_nop 1
	v_cndmask_b32_e64 v18, 0, 32, vcc
	v_ldexp_f32 v17, v17, v18
	v_log_f32_e32 v17, v17
	s_nop 0
	v_mul_f32_e32 v18, 0x3f317217, v17
	v_fma_f32 v18, v17, s29, -v18
	v_fmac_f32_e32 v18, 0x3377d1cf, v17
	v_fmac_f32_e32 v18, 0x3f317217, v17
	v_cmp_lt_f32_e64 s[2:3], |v17|, s27
	s_nop 1
	v_cndmask_b32_e64 v17, v17, v18, s[2:3]
	v_cndmask_b32_e32 v18, 0, v214, vcc
	v_sub_f32_e32 v17, v17, v18
	v_sub_f32_e32 v16, v16, v17
	v_fmamk_f32 v23, v16, 0x3d800000, v22
	ds_read_b128 v[16:19], v127 offset:256
	s_waitcnt lgkmcnt(0)
	v_fma_f32 v24, v106, v16, v122
	v_fmac_f32_e32 v24, v107, v17
	v_fmac_f32_e32 v24, v108, v18
	v_fmac_f32_e32 v24, v109, v19
	ds_read_b128 v[16:19], v127 offset:272
	s_waitcnt lgkmcnt(0)
; DEVI void gla_seq(const Params& p, int l, int item, char* lds) {
;     ...
;     {
;       float run = 0.f;
; #pragma unroll
;       for (int ii = 0; ii < 16; ++ii) {
;         const float* gr_ = gas + (seg * 16 + ii) * 16;
;         float z = ba;
; #pragma unroll
;         for (int r = 0; r < 16; ++r) z += gr_[r] * w2[r];
;         const float ls = fminf(z, 0.f) - __logf(1.f + __expf(-fabsf(z)));
;         run += ls * (1.f / 16.f);
;         bcum[ii] = run;
;       }
;       segtot[seg * 128 + d] = run;
	v_fmac_f32_e32 v24, v110, v16
	v_fmac_f32_e32 v24, v111, v17
	v_fmac_f32_e32 v24, v112, v18
	v_fmac_f32_e32 v24, v113, v19
	ds_read_b128 v[16:19], v127 offset:288
	s_waitcnt lgkmcnt(0)
	v_fmac_f32_e32 v24, v114, v16
	v_fmac_f32_e32 v24, v115, v17
	v_fmac_f32_e32 v24, v116, v18
	v_fmac_f32_e32 v24, v117, v19
	ds_read_b128 v[16:19], v127 offset:304
	s_waitcnt lgkmcnt(0)
	v_fmac_f32_e32 v24, v118, v16
	v_fmac_f32_e32 v24, v119, v17
	v_fmac_f32_e32 v24, v120, v18
	v_fmac_f32_e32 v24, v121, v19
	v_mul_f32_e64 v17, |v24|, s54
	v_exp_f32_e32 v17, v17
	v_min_f32_e32 v16, 0, v24
	v_add_f32_e32 v17, 1.0, v17
	v_cmp_gt_f32_e32 vcc, s59, v17
	s_nop 1
	v_cndmask_b32_e64 v18, 0, 32, vcc
	v_ldexp_f32 v17, v17, v18
	v_log_f32_e32 v17, v17
	s_nop 0
	v_mul_f32_e32 v18, 0x3f317217, v17
	v_fma_f32 v18, v17, s29, -v18
	v_fmac_f32_e32 v18, 0x3377d1cf, v17
	v_fmac_f32_e32 v18, 0x3f317217, v17
	v_cmp_lt_f32_e64 s[2:3], |v17|, s27
	s_nop 1
	v_cndmask_b32_e64 v17, v17, v18, s[2:3]
	v_cndmask_b32_e32 v18, 0, v214, vcc
	v_sub_f32_e32 v17, v17, v18
	v_sub_f32_e32 v16, v16, v17
	v_fmamk_f32 v24, v16, 0x3d800000, v23
	ds_read_b128 v[16:19], v127 offset:320
	s_waitcnt lgkmcnt(0)
	v_fma_f32 v25, v106, v16, v122
	v_fmac_f32_e32 v25, v107, v17
	v_fmac_f32_e32 v25, v108, v18
	v_fmac_f32_e32 v25, v109, v19
	ds_read_b128 v[16:19], v127 offset:336
	s_waitcnt lgkmcnt(0)
	v_fmac_f32_e32 v25, v110, v16
	v_fmac_f32_e32 v25, v111, v17
	v_fmac_f32_e32 v25, v112, v18
	v_fmac_f32_e32 v25, v113, v19
	ds_read_b128 v[16:19], v127 offset:352
	s_waitcnt lgkmcnt(0)
	v_fmac_f32_e32 v25, v114, v16
	v_fmac_f32_e32 v25, v115, v17
	v_fmac_f32_e32 v25, v116, v18
	v_fmac_f32_e32 v25, v117, v19
	ds_read_b128 v[16:19], v127 offset:368
	s_waitcnt lgkmcnt(0)
	v_fmac_f32_e32 v25, v118, v16
	v_fmac_f32_e32 v25, v119, v17
	v_fmac_f32_e32 v25, v120, v18
	v_fmac_f32_e32 v25, v121, v19
	v_mul_f32_e64 v17, |v25|, s54
	v_exp_f32_e32 v17, v17
	v_min_f32_e32 v16, 0, v25
	v_add_f32_e32 v17, 1.0, v17
	v_cmp_gt_f32_e32 vcc, s59, v17
	s_nop 1
	v_cndmask_b32_e64 v18, 0, 32, vcc
	v_ldexp_f32 v17, v17, v18
	v_log_f32_e32 v17, v17
	s_nop 0
	v_mul_f32_e32 v18, 0x3f317217, v17
	v_fma_f32 v18, v17, s29, -v18
	v_fmac_f32_e32 v18, 0x3377d1cf, v17
	v_fmac_f32_e32 v18, 0x3f317217, v17
	v_cmp_lt_f32_e64 s[2:3], |v17|, s27
	s_nop 1
	v_cndmask_b32_e64 v17, v17, v18, s[2:3]
	v_cndmask_b32_e32 v18, 0, v214, vcc
	v_sub_f32_e32 v17, v17, v18
	v_sub_f32_e32 v16, v16, v17
	v_fmamk_f32 v25, v16, 0x3d800000, v24
	ds_read_b128 v[16:19], v127 offset:384
	s_waitcnt lgkmcnt(0)
	v_fma_f32 v26, v106, v16, v122
	v_fmac_f32_e32 v26, v107, v17
	v_fmac_f32_e32 v26, v108, v18
	v_fmac_f32_e32 v26, v109, v19
	ds_read_b128 v[16:19], v127 offset:400
	s_waitcnt lgkmcnt(0)
	v_fmac_f32_e32 v26, v110, v16
	v_fmac_f32_e32 v26, v111, v17
	v_fmac_f32_e32 v26, v112, v18
	v_fmac_f32_e32 v26, v113, v19
	ds_read_b128 v[16:19], v127 offset:416
	s_waitcnt lgkmcnt(0)
	v_fmac_f32_e32 v26, v114, v16
	v_fmac_f32_e32 v26, v115, v17
	v_fmac_f32_e32 v26, v116, v18
	v_fmac_f32_e32 v26, v117, v19
	ds_read_b128 v[16:19], v127 offset:432
	s_waitcnt lgkmcnt(0)
	v_fmac_f32_e32 v26, v118, v16
	v_fmac_f32_e32 v26, v119, v17
	v_fmac_f32_e32 v26, v120, v18
	v_fmac_f32_e32 v26, v121, v19
	v_mul_f32_e64 v17, |v26|, s54
	v_exp_f32_e32 v17, v17
	v_min_f32_e32 v16, 0, v26
	v_add_f32_e32 v17, 1.0, v17
	v_cmp_gt_f32_e32 vcc, s59, v17
	s_nop 1
	v_cndmask_b32_e64 v18, 0, 32, vcc
	v_ldexp_f32 v17, v17, v18
	v_log_f32_e32 v17, v17
	s_nop 0
	v_mul_f32_e32 v18, 0x3f317217, v17
	v_fma_f32 v18, v17, s29, -v18
	v_fmac_f32_e32 v18, 0x3377d1cf, v17
	v_fmac_f32_e32 v18, 0x3f317217, v17
	v_cmp_lt_f32_e64 s[2:3], |v17|, s27
	s_nop 1
	v_cndmask_b32_e64 v17, v17, v18, s[2:3]
	v_cndmask_b32_e32 v18, 0, v214, vcc
	v_sub_f32_e32 v17, v17, v18
	v_sub_f32_e32 v16, v16, v17
	v_fmamk_f32 v26, v16, 0x3d800000, v25
	ds_read_b128 v[16:19], v127 offset:448
	s_waitcnt lgkmcnt(0)
	v_fma_f32 v27, v106, v16, v122
	v_fmac_f32_e32 v27, v107, v17
	v_fmac_f32_e32 v27, v108, v18
	v_fmac_f32_e32 v27, v109, v19
	ds_read_b128 v[16:19], v127 offset:464
	s_waitcnt lgkmcnt(0)
	v_fmac_f32_e32 v27, v110, v16
	v_fmac_f32_e32 v27, v111, v17
	v_fmac_f32_e32 v27, v112, v18
	v_fmac_f32_e32 v27, v113, v19
	ds_read_b128 v[16:19], v127 offset:480
	s_waitcnt lgkmcnt(0)
	v_fmac_f32_e32 v27, v114, v16
	v_fmac_f32_e32 v27, v115, v17
	v_fmac_f32_e32 v27, v116, v18
	v_fmac_f32_e32 v27, v117, v19
	ds_read_b128 v[16:19], v127 offset:496
	s_waitcnt lgkmcnt(0)
	v_fmac_f32_e32 v27, v118, v16
	v_fmac_f32_e32 v27, v119, v17
	v_fmac_f32_e32 v27, v120, v18
	v_fmac_f32_e32 v27, v121, v19
	v_mul_f32_e64 v17, |v27|, s54
	v_exp_f32_e32 v17, v17
	v_min_f32_e32 v16, 0, v27
	v_add_f32_e32 v17, 1.0, v17
	v_cmp_gt_f32_e32 vcc, s59, v17
	s_nop 1
	v_cndmask_b32_e64 v18, 0, 32, vcc
	v_ldexp_f32 v17, v17, v18
	v_log_f32_e32 v17, v17
	s_nop 0
	v_mul_f32_e32 v18, 0x3f317217, v17
	v_fma_f32 v18, v17, s29, -v18
	v_fmac_f32_e32 v18, 0x3377d1cf, v17
	v_fmac_f32_e32 v18, 0x3f317217, v17
	v_cmp_lt_f32_e64 s[2:3], |v17|, s27
	s_nop 1
	v_cndmask_b32_e64 v17, v17, v18, s[2:3]
	v_cndmask_b32_e32 v18, 0, v214, vcc
	v_sub_f32_e32 v17, v17, v18
	v_sub_f32_e32 v16, v16, v17
	v_fmamk_f32 v27, v16, 0x3d800000, v26
	ds_read_b128 v[16:19], v127 offset:512
	s_waitcnt lgkmcnt(0)
	v_fma_f32 v28, v106, v16, v122
	v_fmac_f32_e32 v28, v107, v17
	v_fmac_f32_e32 v28, v108, v18
	v_fmac_f32_e32 v28, v109, v19
	ds_read_b128 v[16:19], v127 offset:528
	s_waitcnt lgkmcnt(0)
	v_fmac_f32_e32 v28, v110, v16
	v_fmac_f32_e32 v28, v111, v17
	v_fmac_f32_e32 v28, v112, v18
	v_fmac_f32_e32 v28, v113, v19
	ds_read_b128 v[16:19], v127 offset:544
	s_waitcnt lgkmcnt(0)
; DEVI void gla_seq(const Params& p, int l, int item, char* lds) {
;     ...
;     {
;       float run = 0.f;
; #pragma unroll
;       for (int ii = 0; ii < 16; ++ii) {
;         const float* gr_ = gas + (seg * 16 + ii) * 16;
;         float z = ba;
; #pragma unroll
;         for (int r = 0; r < 16; ++r) z += gr_[r] * w2[r];
;         const float ls = fminf(z, 0.f) - __logf(1.f + __expf(-fabsf(z)));
;         run += ls * (1.f / 16.f);
;         bcum[ii] = run;
;       }
;       segtot[seg * 128 + d] = run;
	v_fmac_f32_e32 v28, v114, v16
	v_fmac_f32_e32 v28, v115, v17
	v_fmac_f32_e32 v28, v116, v18
	v_fmac_f32_e32 v28, v117, v19
	ds_read_b128 v[16:19], v127 offset:560
	s_waitcnt lgkmcnt(0)
	v_fmac_f32_e32 v28, v118, v16
	v_fmac_f32_e32 v28, v119, v17
	v_fmac_f32_e32 v28, v120, v18
	v_fmac_f32_e32 v28, v121, v19
	v_mul_f32_e64 v17, |v28|, s54
	v_exp_f32_e32 v17, v17
	v_min_f32_e32 v16, 0, v28
	v_add_f32_e32 v17, 1.0, v17
	v_cmp_gt_f32_e32 vcc, s59, v17
	s_nop 1
	v_cndmask_b32_e64 v18, 0, 32, vcc
	v_ldexp_f32 v17, v17, v18
	v_log_f32_e32 v17, v17
	s_nop 0
	v_mul_f32_e32 v18, 0x3f317217, v17
	v_fma_f32 v18, v17, s29, -v18
	v_fmac_f32_e32 v18, 0x3377d1cf, v17
	v_fmac_f32_e32 v18, 0x3f317217, v17
	v_cmp_lt_f32_e64 s[2:3], |v17|, s27
	s_nop 1
	v_cndmask_b32_e64 v17, v17, v18, s[2:3]
	v_cndmask_b32_e32 v18, 0, v214, vcc
	v_sub_f32_e32 v17, v17, v18
	v_sub_f32_e32 v16, v16, v17
	v_fmamk_f32 v28, v16, 0x3d800000, v27
	ds_read_b128 v[16:19], v127 offset:576
	s_waitcnt lgkmcnt(0)
	v_fma_f32 v29, v106, v16, v122
	v_fmac_f32_e32 v29, v107, v17
	v_fmac_f32_e32 v29, v108, v18
	v_fmac_f32_e32 v29, v109, v19
	ds_read_b128 v[16:19], v127 offset:592
	s_waitcnt lgkmcnt(0)
	v_fmac_f32_e32 v29, v110, v16
	v_fmac_f32_e32 v29, v111, v17
	v_fmac_f32_e32 v29, v112, v18
	v_fmac_f32_e32 v29, v113, v19
	ds_read_b128 v[16:19], v127 offset:608
	s_waitcnt lgkmcnt(0)
	v_fmac_f32_e32 v29, v114, v16
	v_fmac_f32_e32 v29, v115, v17
	v_fmac_f32_e32 v29, v116, v18
	v_fmac_f32_e32 v29, v117, v19
	ds_read_b128 v[16:19], v127 offset:624
	s_waitcnt lgkmcnt(0)
	v_fmac_f32_e32 v29, v118, v16
	v_fmac_f32_e32 v29, v119, v17
	v_fmac_f32_e32 v29, v120, v18
	v_fmac_f32_e32 v29, v121, v19
	v_mul_f32_e64 v17, |v29|, s54
	v_exp_f32_e32 v17, v17
	v_min_f32_e32 v16, 0, v29
	v_add_f32_e32 v17, 1.0, v17
	v_cmp_gt_f32_e32 vcc, s59, v17
	s_nop 1
	v_cndmask_b32_e64 v18, 0, 32, vcc
	v_ldexp_f32 v17, v17, v18
	v_log_f32_e32 v17, v17
	s_nop 0
	v_mul_f32_e32 v18, 0x3f317217, v17
	v_fma_f32 v18, v17, s29, -v18
	v_fmac_f32_e32 v18, 0x3377d1cf, v17
	v_fmac_f32_e32 v18, 0x3f317217, v17
	v_cmp_lt_f32_e64 s[2:3], |v17|, s27
	s_nop 1
	v_cndmask_b32_e64 v17, v17, v18, s[2:3]
	v_cndmask_b32_e32 v18, 0, v214, vcc
	v_sub_f32_e32 v17, v17, v18
	v_sub_f32_e32 v16, v16, v17
	v_fmamk_f32 v29, v16, 0x3d800000, v28
	ds_read_b128 v[16:19], v127 offset:640
	s_waitcnt lgkmcnt(0)
	v_fma_f32 v30, v106, v16, v122
	v_fmac_f32_e32 v30, v107, v17
	v_fmac_f32_e32 v30, v108, v18
	v_fmac_f32_e32 v30, v109, v19
	ds_read_b128 v[16:19], v127 offset:656
	s_waitcnt lgkmcnt(0)
	v_fmac_f32_e32 v30, v110, v16
	v_fmac_f32_e32 v30, v111, v17
	v_fmac_f32_e32 v30, v112, v18
	v_fmac_f32_e32 v30, v113, v19
	ds_read_b128 v[16:19], v127 offset:672
	s_waitcnt lgkmcnt(0)
	v_fmac_f32_e32 v30, v114, v16
	v_fmac_f32_e32 v30, v115, v17
	v_fmac_f32_e32 v30, v116, v18
	v_fmac_f32_e32 v30, v117, v19
	ds_read_b128 v[16:19], v127 offset:688
	s_waitcnt lgkmcnt(0)
	v_fmac_f32_e32 v30, v118, v16
	v_fmac_f32_e32 v30, v119, v17
	v_fmac_f32_e32 v30, v120, v18
	v_fmac_f32_e32 v30, v121, v19
	v_mul_f32_e64 v17, |v30|, s54
	v_exp_f32_e32 v17, v17
	v_min_f32_e32 v16, 0, v30
	v_add_f32_e32 v17, 1.0, v17
	v_cmp_gt_f32_e32 vcc, s59, v17
	s_nop 1
	v_cndmask_b32_e64 v18, 0, 32, vcc
	v_ldexp_f32 v17, v17, v18
	v_log_f32_e32 v17, v17
	s_nop 0
	v_mul_f32_e32 v18, 0x3f317217, v17
	v_fma_f32 v18, v17, s29, -v18
	v_fmac_f32_e32 v18, 0x3377d1cf, v17
	v_fmac_f32_e32 v18, 0x3f317217, v17
	v_cmp_lt_f32_e64 s[2:3], |v17|, s27
	s_nop 1
	v_cndmask_b32_e64 v17, v17, v18, s[2:3]
	v_cndmask_b32_e32 v18, 0, v214, vcc
	v_sub_f32_e32 v17, v17, v18
	v_sub_f32_e32 v16, v16, v17
	v_fmamk_f32 v30, v16, 0x3d800000, v29
	ds_read_b128 v[16:19], v127 offset:704
	s_waitcnt lgkmcnt(0)
	v_fma_f32 v31, v106, v16, v122
	v_fmac_f32_e32 v31, v107, v17
	v_fmac_f32_e32 v31, v108, v18
	v_fmac_f32_e32 v31, v109, v19
	ds_read_b128 v[16:19], v127 offset:720
	s_waitcnt lgkmcnt(0)
	v_fmac_f32_e32 v31, v110, v16
	v_fmac_f32_e32 v31, v111, v17
	v_fmac_f32_e32 v31, v112, v18
	v_fmac_f32_e32 v31, v113, v19
	ds_read_b128 v[16:19], v127 offset:736
	s_waitcnt lgkmcnt(0)
	v_fmac_f32_e32 v31, v114, v16
	v_fmac_f32_e32 v31, v115, v17
	v_fmac_f32_e32 v31, v116, v18
	v_fmac_f32_e32 v31, v117, v19
	ds_read_b128 v[16:19], v127 offset:752
	s_waitcnt lgkmcnt(0)
	v_fmac_f32_e32 v31, v118, v16
	v_fmac_f32_e32 v31, v119, v17
	v_fmac_f32_e32 v31, v120, v18
	v_fmac_f32_e32 v31, v121, v19
	v_mul_f32_e64 v17, |v31|, s54
	v_exp_f32_e32 v17, v17
	v_min_f32_e32 v16, 0, v31
	v_add_f32_e32 v17, 1.0, v17
	v_cmp_gt_f32_e32 vcc, s59, v17
	s_nop 1
	v_cndmask_b32_e64 v18, 0, 32, vcc
	v_ldexp_f32 v17, v17, v18
	v_log_f32_e32 v17, v17
	s_nop 0
	v_mul_f32_e32 v18, 0x3f317217, v17
	v_fma_f32 v18, v17, s29, -v18
	v_fmac_f32_e32 v18, 0x3377d1cf, v17
	v_fmac_f32_e32 v18, 0x3f317217, v17
	v_cmp_lt_f32_e64 s[2:3], |v17|, s27
	s_nop 1
	v_cndmask_b32_e64 v17, v17, v18, s[2:3]
	v_cndmask_b32_e32 v18, 0, v214, vcc
	v_sub_f32_e32 v17, v17, v18
	v_sub_f32_e32 v16, v16, v17
	v_fmamk_f32 v31, v16, 0x3d800000, v30
	ds_read_b128 v[16:19], v127 offset:768
	s_waitcnt lgkmcnt(0)
	v_fma_f32 v32, v106, v16, v122
	v_fmac_f32_e32 v32, v107, v17
	v_fmac_f32_e32 v32, v108, v18
	v_fmac_f32_e32 v32, v109, v19
	ds_read_b128 v[16:19], v127 offset:784
	s_waitcnt lgkmcnt(0)
	v_fmac_f32_e32 v32, v110, v16
	v_fmac_f32_e32 v32, v111, v17
	v_fmac_f32_e32 v32, v112, v18
	v_fmac_f32_e32 v32, v113, v19
	ds_read_b128 v[16:19], v127 offset:800
	s_waitcnt lgkmcnt(0)
	v_fmac_f32_e32 v32, v114, v16
	v_fmac_f32_e32 v32, v115, v17
	v_fmac_f32_e32 v32, v116, v18
	v_fmac_f32_e32 v32, v117, v19
	ds_read_b128 v[16:19], v127 offset:816
	s_waitcnt lgkmcnt(0)
; DEVI void gla_seq(const Params& p, int l, int item, char* lds) {
;     ...
;     {
;       float run = 0.f;
; #pragma unroll
;       for (int ii = 0; ii < 16; ++ii) {
;         const float* gr_ = gas + (seg * 16 + ii) * 16;
;         float z = ba;
; #pragma unroll
;         for (int r = 0; r < 16; ++r) z += gr_[r] * w2[r];
;         const float ls = fminf(z, 0.f) - __logf(1.f + __expf(-fabsf(z)));
;         run += ls * (1.f / 16.f);
;         bcum[ii] = run;
;       }
;       segtot[seg * 128 + d] = run;
;     }
;     __syncthreads();
	v_fmac_f32_e32 v32, v118, v16
	v_fmac_f32_e32 v32, v119, v17
	v_fmac_f32_e32 v32, v120, v18
	v_fmac_f32_e32 v32, v121, v19
	v_mul_f32_e64 v17, |v32|, s54
	v_exp_f32_e32 v17, v17
	v_min_f32_e32 v16, 0, v32
	v_add_f32_e32 v17, 1.0, v17
	v_cmp_gt_f32_e32 vcc, s59, v17
	s_nop 1
	v_cndmask_b32_e64 v18, 0, 32, vcc
	v_ldexp_f32 v17, v17, v18
	v_log_f32_e32 v17, v17
	s_nop 0
	v_mul_f32_e32 v18, 0x3f317217, v17
	v_fma_f32 v18, v17, s29, -v18
	v_fmac_f32_e32 v18, 0x3377d1cf, v17
	v_fmac_f32_e32 v18, 0x3f317217, v17
	v_cmp_lt_f32_e64 s[2:3], |v17|, s27
	s_nop 1
	v_cndmask_b32_e64 v17, v17, v18, s[2:3]
	v_cndmask_b32_e32 v18, 0, v214, vcc
	v_sub_f32_e32 v17, v17, v18
	v_sub_f32_e32 v16, v16, v17
	v_fmamk_f32 v32, v16, 0x3d800000, v31
	ds_read_b128 v[16:19], v127 offset:832
	s_waitcnt lgkmcnt(0)
	v_fma_f32 v33, v106, v16, v122
	v_fmac_f32_e32 v33, v107, v17
	v_fmac_f32_e32 v33, v108, v18
	v_fmac_f32_e32 v33, v109, v19
	ds_read_b128 v[16:19], v127 offset:848
	s_waitcnt lgkmcnt(0)
	v_fmac_f32_e32 v33, v110, v16
	v_fmac_f32_e32 v33, v111, v17
	v_fmac_f32_e32 v33, v112, v18
	v_fmac_f32_e32 v33, v113, v19
	ds_read_b128 v[16:19], v127 offset:864
	s_waitcnt lgkmcnt(0)
	v_fmac_f32_e32 v33, v114, v16
	v_fmac_f32_e32 v33, v115, v17
	v_fmac_f32_e32 v33, v116, v18
	v_fmac_f32_e32 v33, v117, v19
	ds_read_b128 v[16:19], v127 offset:880
	s_waitcnt lgkmcnt(0)
	v_fmac_f32_e32 v33, v118, v16
	v_fmac_f32_e32 v33, v119, v17
	v_fmac_f32_e32 v33, v120, v18
	v_fmac_f32_e32 v33, v121, v19
	v_mul_f32_e64 v17, |v33|, s54
	v_exp_f32_e32 v17, v17
	v_min_f32_e32 v16, 0, v33
	v_add_f32_e32 v17, 1.0, v17
	v_cmp_gt_f32_e32 vcc, s59, v17
	s_nop 1
	v_cndmask_b32_e64 v18, 0, 32, vcc
	v_ldexp_f32 v17, v17, v18
	v_log_f32_e32 v17, v17
	s_nop 0
	v_mul_f32_e32 v18, 0x3f317217, v17
	v_fma_f32 v18, v17, s29, -v18
	v_fmac_f32_e32 v18, 0x3377d1cf, v17
	v_fmac_f32_e32 v18, 0x3f317217, v17
	v_cmp_lt_f32_e64 s[2:3], |v17|, s27
	s_nop 1
	v_cndmask_b32_e64 v17, v17, v18, s[2:3]
	v_cndmask_b32_e32 v18, 0, v214, vcc
	v_sub_f32_e32 v17, v17, v18
	v_sub_f32_e32 v16, v16, v17
	v_fmamk_f32 v33, v16, 0x3d800000, v32
	ds_read_b128 v[16:19], v127 offset:896
	s_waitcnt lgkmcnt(0)
	v_fma_f32 v34, v106, v16, v122
	v_fmac_f32_e32 v34, v107, v17
	v_fmac_f32_e32 v34, v108, v18
	v_fmac_f32_e32 v34, v109, v19
	ds_read_b128 v[16:19], v127 offset:912
	s_waitcnt lgkmcnt(0)
	v_fmac_f32_e32 v34, v110, v16
	v_fmac_f32_e32 v34, v111, v17
	v_fmac_f32_e32 v34, v112, v18
	v_fmac_f32_e32 v34, v113, v19
	ds_read_b128 v[16:19], v127 offset:928
	s_waitcnt lgkmcnt(0)
	v_fmac_f32_e32 v34, v114, v16
	v_fmac_f32_e32 v34, v115, v17
	v_fmac_f32_e32 v34, v116, v18
	v_fmac_f32_e32 v34, v117, v19
	ds_read_b128 v[16:19], v127 offset:944
	s_waitcnt lgkmcnt(0)
	v_fmac_f32_e32 v34, v118, v16
	v_fmac_f32_e32 v34, v119, v17
	v_fmac_f32_e32 v34, v120, v18
	v_fmac_f32_e32 v34, v121, v19
	v_mul_f32_e64 v17, |v34|, s54
	v_exp_f32_e32 v17, v17
	v_min_f32_e32 v16, 0, v34
	v_add_f32_e32 v17, 1.0, v17
	v_cmp_gt_f32_e32 vcc, s59, v17
	s_nop 1
	v_cndmask_b32_e64 v18, 0, 32, vcc
	v_ldexp_f32 v17, v17, v18
	v_log_f32_e32 v17, v17
	s_nop 0
	v_mul_f32_e32 v18, 0x3f317217, v17
	v_fma_f32 v18, v17, s29, -v18
	v_fmac_f32_e32 v18, 0x3377d1cf, v17
	v_fmac_f32_e32 v18, 0x3f317217, v17
	v_cmp_lt_f32_e64 s[2:3], |v17|, s27
	s_nop 1
	v_cndmask_b32_e64 v17, v17, v18, s[2:3]
	v_cndmask_b32_e32 v18, 0, v214, vcc
	v_sub_f32_e32 v17, v17, v18
	v_sub_f32_e32 v16, v16, v17
	v_fmamk_f32 v34, v16, 0x3d800000, v33
	ds_read_b128 v[16:19], v127 offset:960
	s_waitcnt lgkmcnt(0)
	v_fma_f32 v35, v106, v16, v122
	v_fmac_f32_e32 v35, v107, v17
	v_fmac_f32_e32 v35, v108, v18
	v_fmac_f32_e32 v35, v109, v19
	ds_read_b128 v[16:19], v127 offset:976
	s_waitcnt lgkmcnt(0)
	v_fmac_f32_e32 v35, v110, v16
	v_fmac_f32_e32 v35, v111, v17
	v_fmac_f32_e32 v35, v112, v18
	v_fmac_f32_e32 v35, v113, v19
	ds_read_b128 v[16:19], v127 offset:992
	s_waitcnt lgkmcnt(0)
	v_fmac_f32_e32 v35, v114, v16
	v_fmac_f32_e32 v35, v115, v17
	v_fmac_f32_e32 v35, v116, v18
	v_fmac_f32_e32 v35, v117, v19
	ds_read_b128 v[16:19], v127 offset:1008
	s_waitcnt lgkmcnt(0)
	v_fmac_f32_e32 v35, v118, v16
	v_fmac_f32_e32 v35, v119, v17
	v_fmac_f32_e32 v35, v120, v18
	v_fmac_f32_e32 v35, v121, v19
	v_mul_f32_e64 v17, |v35|, s54
	v_exp_f32_e32 v17, v17
	v_min_f32_e32 v16, 0, v35
	v_add_f32_e32 v17, 1.0, v17
	v_cmp_gt_f32_e32 vcc, s59, v17
	s_nop 1
	v_cndmask_b32_e64 v18, 0, 32, vcc
	v_ldexp_f32 v17, v17, v18
	v_log_f32_e32 v17, v17
	s_nop 0
	v_mul_f32_e32 v18, 0x3f317217, v17
	v_fma_f32 v18, v17, s29, -v18
	v_fmac_f32_e32 v18, 0x3377d1cf, v17
	v_fmac_f32_e32 v18, 0x3f317217, v17
	v_cmp_lt_f32_e64 s[2:3], |v17|, s27
	s_nop 1
	v_cndmask_b32_e64 v17, v17, v18, s[2:3]
	v_cndmask_b32_e32 v18, 0, v214, vcc
	v_sub_f32_e32 v17, v17, v18
	v_sub_f32_e32 v16, v16, v17
	v_fmamk_f32 v35, v16, 0x3d800000, v34
	ds_write_b32 v128, v35
	s_waitcnt lgkmcnt(0)
	s_barrier
; DEVI u16 f2bf(float f) { return (u16)(cvtpk(f, 0.f) & 0xffffu); }
; DEVI float bf2f(u16 h) { return __uint_as_float(((unsigned)h) << 16); }
; DEVI void gla_seq(const Params& p, int l, int item, char* lds) {
;     ...
;     {
;       float pre = 0.f, tot = 0.f;
; #pragma unroll
;       for (int s_ = 0; s_ < 4; ++s_) { const float v = segtot[s_ * 128 + d]; tot += v; if (s_ < seg) pre += v; }
;       const float etot = __expf(tot);
;       if (seg == 0) ebl[d] = etot;
; #pragma unroll
;       for (int ii = 0; ii < 16; ++ii) {
;         const int i = seg * 16 + ii;
;         const float bb = bcum[ii] + pre;
;         const int so = i * 256 + (((d >> 3) ^ (i & 7)) << 4) + (d & 7) * 2;
;         const float q = bf2f(*(const u16*)(qs + so)), k = bf2f(*(const u16*)(ks + so));
;         const float eb = __expf(bb), ieb = __frcp_rn(eb);
;         *(u16*)(qs + so) = f2bf(q * eb);
;         *(u16*)(ks + so) = f2bf(k * ieb);
;         *(u16*)(kT + d * 144 + i * 2) = f2bf(k * (etot * ieb));
;       }
	ds_read2st64_b32 v[16:17], v129 offset1:2
	ds_read2st64_b32 v[18:19], v129 offset0:4 offset1:6
	s_waitcnt lgkmcnt(1)
	v_add_f32_e32 v36, 0, v16
	v_add_f32_e32 v16, v36, v17
	s_waitcnt lgkmcnt(0)
	v_add_f32_e32 v16, v16, v18
	v_add_f32_e32 v16, v16, v19
	v_mul_f32_e32 v16, 0x3fb8aa3b, v16
	v_exp_f32_e32 v16, v16
	s_and_saveexec_b64 s[2:3], s[6:7]
	ds_write_b32 v136, v16
	s_or_b64 exec, exec, s[2:3]
	v_cndmask_b32_e64 v36, 0, v36, s[10:11]
	v_add_f32_e32 v17, v17, v36
	v_cndmask_b32_e64 v17, v36, v17, s[12:13]
	v_add_f32_e32 v18, v18, v17
	v_cndmask_b32_e64 v17, v17, v18, s[14:15]
	v_add_f32_e32 v18, v19, v17
	v_cndmask_b32_e64 v17, v17, v18, s[16:17]
	v_add_f32_e32 v18, v20, v17
	v_mul_f32_e32 v18, 0x3fb8aa3b, v18
	v_exp_f32_e64 v36, -v18
	v_exp_f32_e32 v18, v18
	ds_read_u16 v19, v154
	ds_read_u16 v20, v154 offset:16384
	v_add_u32_e32 v187, v133, v131
	s_waitcnt lgkmcnt(1)
	v_lshlrev_b32_e32 v19, 16, v19
	s_waitcnt lgkmcnt(0)
	v_lshlrev_b32_e32 v20, 16, v20
	v_mul_f32_e32 v18, v18, v19
	v_cvt_pk_bf16_f32 v18, v18, s0
	ds_write_b16 v154, v18
	v_mul_f32_e32 v18, v36, v20
	v_cvt_pk_bf16_f32 v18, v18, s0
	ds_write_b16 v154, v18 offset:16384
	v_mul_f32_e32 v18, v16, v36
	v_mul_f32_e32 v18, v18, v20
	v_cvt_pk_bf16_f32 v18, v18, s0
	v_add_u32_e32 v19, v130, v132
	ds_write_b16 v19, v18 offset:32768
	v_add_f32_e32 v18, v21, v17
	v_mul_f32_e32 v18, 0x3fb8aa3b, v18
	v_exp_f32_e64 v21, -v18
	v_exp_f32_e32 v18, v18
	ds_read_u16 v19, v155
	ds_read_u16 v20, v155 offset:16384
	s_waitcnt lgkmcnt(1)
	v_lshlrev_b32_e32 v19, 16, v19
	s_waitcnt lgkmcnt(0)
	v_lshlrev_b32_e32 v20, 16, v20
	v_mul_f32_e32 v18, v18, v19
	v_cvt_pk_bf16_f32 v18, v18, s0
	ds_write_b16 v155, v18
	v_mul_f32_e32 v18, v21, v20
	v_cvt_pk_bf16_f32 v18, v18, s0
	ds_write_b16 v155, v18 offset:16384
	v_mul_f32_e32 v18, v16, v21
	v_mul_f32_e32 v18, v18, v20
	v_cvt_pk_bf16_f32 v18, v18, s0
	ds_write_b16 v156, v18 offset:32768
	v_add_f32_e32 v18, v22, v17
	v_mul_f32_e32 v18, 0x3fb8aa3b, v18
	v_exp_f32_e64 v21, -v18
	v_exp_f32_e32 v18, v18
	ds_read_u16 v19, v157
	ds_read_u16 v20, v157 offset:16384
	s_waitcnt lgkmcnt(1)
	v_lshlrev_b32_e32 v19, 16, v19
	s_waitcnt lgkmcnt(0)
	v_lshlrev_b32_e32 v20, 16, v20
	v_mul_f32_e32 v18, v18, v19
	v_cvt_pk_bf16_f32 v18, v18, s0
	ds_write_b16 v157, v18
	v_mul_f32_e32 v18, v21, v20
	v_cvt_pk_bf16_f32 v18, v18, s0
	ds_write_b16 v157, v18 offset:16384
	v_mul_f32_e32 v18, v16, v21
	v_mul_f32_e32 v18, v18, v20
	v_cvt_pk_bf16_f32 v18, v18, s0
	ds_write_b16 v158, v18 offset:32768
	v_add_f32_e32 v18, v23, v17
	v_mul_f32_e32 v18, 0x3fb8aa3b, v18
	v_exp_f32_e64 v21, -v18
	v_exp_f32_e32 v18, v18
	ds_read_u16 v19, v159
	ds_read_u16 v20, v159 offset:16384
	s_waitcnt lgkmcnt(1)
	v_lshlrev_b32_e32 v19, 16, v19
	s_waitcnt lgkmcnt(0)
	v_lshlrev_b32_e32 v20, 16, v20
	v_mul_f32_e32 v18, v18, v19
	v_cvt_pk_bf16_f32 v18, v18, s0
	ds_write_b16 v159, v18
	v_mul_f32_e32 v18, v21, v20
	v_cvt_pk_bf16_f32 v18, v18, s0
	ds_write_b16 v159, v18 offset:16384
	v_mul_f32_e32 v18, v16, v21
	v_mul_f32_e32 v18, v18, v20
	v_cvt_pk_bf16_f32 v18, v18, s0
	ds_write_b16 v160, v18 offset:32768
	v_add_f32_e32 v18, v24, v17
	v_mul_f32_e32 v18, 0x3fb8aa3b, v18
	v_exp_f32_e64 v21, -v18
	v_exp_f32_e32 v18, v18
	ds_read_u16 v19, v161
	ds_read_u16 v20, v161 offset:16384
	s_waitcnt lgkmcnt(1)
	v_lshlrev_b32_e32 v19, 16, v19
	s_waitcnt lgkmcnt(0)
	v_lshlrev_b32_e32 v20, 16, v20
	v_mul_f32_e32 v18, v18, v19
	v_cvt_pk_bf16_f32 v18, v18, s0
	ds_write_b16 v161, v18
	v_mul_f32_e32 v18, v21, v20
	v_cvt_pk_bf16_f32 v18, v18, s0
	ds_write_b16 v161, v18 offset:16384
	v_mul_f32_e32 v18, v16, v21
	v_mul_f32_e32 v18, v18, v20
	v_cvt_pk_bf16_f32 v18, v18, s0
	ds_write_b16 v162, v18 offset:32768
	v_add_f32_e32 v18, v25, v17
	v_mul_f32_e32 v18, 0x3fb8aa3b, v18
	v_exp_f32_e64 v21, -v18
	v_exp_f32_e32 v18, v18
	ds_read_u16 v19, v163
	ds_read_u16 v20, v163 offset:16384
	s_waitcnt lgkmcnt(1)
	v_lshlrev_b32_e32 v19, 16, v19
	s_waitcnt lgkmcnt(0)
	v_lshlrev_b32_e32 v20, 16, v20
	v_mul_f32_e32 v18, v18, v19
	v_cvt_pk_bf16_f32 v18, v18, s0
	ds_write_b16 v163, v18
	v_mul_f32_e32 v18, v21, v20
	v_cvt_pk_bf16_f32 v18, v18, s0
	ds_write_b16 v163, v18 offset:16384
	v_mul_f32_e32 v18, v16, v21
	v_mul_f32_e32 v18, v18, v20
	v_cvt_pk_bf16_f32 v18, v18, s0
	ds_write_b16 v164, v18 offset:32768
	v_add_f32_e32 v18, v26, v17
	v_mul_f32_e32 v18, 0x3fb8aa3b, v18
	v_exp_f32_e64 v21, -v18
	v_exp_f32_e32 v18, v18
	ds_read_u16 v19, v165
	ds_read_u16 v20, v165 offset:16384
	s_waitcnt lgkmcnt(1)
	v_lshlrev_b32_e32 v19, 16, v19
	s_waitcnt lgkmcnt(0)
	v_lshlrev_b32_e32 v20, 16, v20
	v_mul_f32_e32 v18, v18, v19
	v_cvt_pk_bf16_f32 v18, v18, s0
	ds_write_b16 v165, v18
	v_mul_f32_e32 v18, v21, v20
	v_cvt_pk_bf16_f32 v18, v18, s0
	ds_write_b16 v165, v18 offset:16384
	v_mul_f32_e32 v18, v16, v21
	v_mul_f32_e32 v18, v18, v20
	v_cvt_pk_bf16_f32 v18, v18, s0
	ds_write_b16 v166, v18 offset:32768
	v_add_f32_e32 v18, v27, v17
	v_mul_f32_e32 v18, 0x3fb8aa3b, v18
	v_exp_f32_e64 v21, -v18
	v_exp_f32_e32 v18, v18
	ds_read_u16 v19, v167
	ds_read_u16 v20, v167 offset:16384
	s_waitcnt lgkmcnt(1)
	v_lshlrev_b32_e32 v19, 16, v19
	s_waitcnt lgkmcnt(0)
	v_lshlrev_b32_e32 v20, 16, v20
	v_mul_f32_e32 v18, v18, v19
	v_cvt_pk_bf16_f32 v18, v18, s0
	ds_write_b16 v167, v18
	v_mul_f32_e32 v18, v21, v20
	v_cvt_pk_bf16_f32 v18, v18, s0
	ds_write_b16 v167, v18 offset:16384
	v_mul_f32_e32 v18, v16, v21
	v_mul_f32_e32 v18, v18, v20
	v_cvt_pk_bf16_f32 v18, v18, s0
	ds_write_b16 v168, v18 offset:32768
	v_add_f32_e32 v18, v28, v17
	v_mul_f32_e32 v18, 0x3fb8aa3b, v18
	v_exp_f32_e64 v21, -v18
	v_exp_f32_e32 v18, v18
	ds_read_u16 v19, v169
	ds_read_u16 v20, v169 offset:16384
	s_waitcnt lgkmcnt(1)
; DEVI u16 f2bf(float f) { return (u16)(cvtpk(f, 0.f) & 0xffffu); }
; DEVI float bf2f(u16 h) { return __uint_as_float(((unsigned)h) << 16); }
; DEVI void gla_seq(const Params& p, int l, int item, char* lds) {
;     ...
;     {
;       float pre = 0.f, tot = 0.f;
; #pragma unroll
;       for (int s_ = 0; s_ < 4; ++s_) { const float v = segtot[s_ * 128 + d]; tot += v; if (s_ < seg) pre += v; }
;       const float etot = __expf(tot);
;       if (seg == 0) ebl[d] = etot;
; #pragma unroll
;       for (int ii = 0; ii < 16; ++ii) {
;         const int i = seg * 16 + ii;
;         const float bb = bcum[ii] + pre;
;         const int so = i * 256 + (((d >> 3) ^ (i & 7)) << 4) + (d & 7) * 2;
;         const float q = bf2f(*(const u16*)(qs + so)), k = bf2f(*(const u16*)(ks + so));
;         const float eb = __expf(bb), ieb = __frcp_rn(eb);
;         *(u16*)(qs + so) = f2bf(q * eb);
;         *(u16*)(ks + so) = f2bf(k * ieb);
;         *(u16*)(kT + d * 144 + i * 2) = f2bf(k * (etot * ieb));
;       }
;     }
;     __syncthreads();
;     const char* sTc = sT + cur * 16384; char* sTn = sT + (cur ^ 1) * 16384;
;     if (wid < 4) {
	v_lshlrev_b32_e32 v19, 16, v19
	s_waitcnt lgkmcnt(0)
	v_lshlrev_b32_e32 v20, 16, v20
	v_mul_f32_e32 v18, v18, v19
	v_cvt_pk_bf16_f32 v18, v18, s0
	ds_write_b16 v169, v18
	v_mul_f32_e32 v18, v21, v20
	v_cvt_pk_bf16_f32 v18, v18, s0
	ds_write_b16 v169, v18 offset:16384
	v_mul_f32_e32 v18, v16, v21
	v_mul_f32_e32 v18, v18, v20
	v_cvt_pk_bf16_f32 v18, v18, s0
	ds_write_b16 v170, v18 offset:32768
	v_add_f32_e32 v18, v29, v17
	v_mul_f32_e32 v18, 0x3fb8aa3b, v18
	v_exp_f32_e64 v21, -v18
	v_exp_f32_e32 v18, v18
	ds_read_u16 v19, v171
	ds_read_u16 v20, v171 offset:16384
	s_waitcnt lgkmcnt(1)
	v_lshlrev_b32_e32 v19, 16, v19
	s_waitcnt lgkmcnt(0)
	v_lshlrev_b32_e32 v20, 16, v20
	v_mul_f32_e32 v18, v18, v19
	v_cvt_pk_bf16_f32 v18, v18, s0
	ds_write_b16 v171, v18
	v_mul_f32_e32 v18, v21, v20
	v_cvt_pk_bf16_f32 v18, v18, s0
	ds_write_b16 v171, v18 offset:16384
	v_mul_f32_e32 v18, v16, v21
	v_mul_f32_e32 v18, v18, v20
	v_cvt_pk_bf16_f32 v18, v18, s0
	ds_write_b16 v172, v18 offset:32768
	v_add_f32_e32 v18, v30, v17
	v_mul_f32_e32 v18, 0x3fb8aa3b, v18
	v_exp_f32_e64 v21, -v18
	v_exp_f32_e32 v18, v18
	ds_read_u16 v19, v173
	ds_read_u16 v20, v173 offset:16384
	s_waitcnt lgkmcnt(1)
	v_lshlrev_b32_e32 v19, 16, v19
	s_waitcnt lgkmcnt(0)
	v_lshlrev_b32_e32 v20, 16, v20
	v_mul_f32_e32 v18, v18, v19
	v_cvt_pk_bf16_f32 v18, v18, s0
	ds_write_b16 v173, v18
	v_mul_f32_e32 v18, v21, v20
	v_cvt_pk_bf16_f32 v18, v18, s0
	ds_write_b16 v173, v18 offset:16384
	v_mul_f32_e32 v18, v16, v21
	v_mul_f32_e32 v18, v18, v20
	v_cvt_pk_bf16_f32 v18, v18, s0
	ds_write_b16 v174, v18 offset:32768
	v_add_f32_e32 v18, v31, v17
	v_mul_f32_e32 v18, 0x3fb8aa3b, v18
	v_exp_f32_e64 v21, -v18
	v_exp_f32_e32 v18, v18
	ds_read_u16 v19, v175
	ds_read_u16 v20, v175 offset:16384
	s_waitcnt lgkmcnt(1)
	v_lshlrev_b32_e32 v19, 16, v19
	s_waitcnt lgkmcnt(0)
	v_lshlrev_b32_e32 v20, 16, v20
	v_mul_f32_e32 v18, v18, v19
	v_cvt_pk_bf16_f32 v18, v18, s0
	ds_write_b16 v175, v18
	v_mul_f32_e32 v18, v21, v20
	v_cvt_pk_bf16_f32 v18, v18, s0
	ds_write_b16 v175, v18 offset:16384
	v_mul_f32_e32 v18, v16, v21
	v_mul_f32_e32 v18, v18, v20
	v_cvt_pk_bf16_f32 v18, v18, s0
	ds_write_b16 v176, v18 offset:32768
	v_add_f32_e32 v18, v32, v17
	v_mul_f32_e32 v18, 0x3fb8aa3b, v18
	v_exp_f32_e64 v21, -v18
	v_exp_f32_e32 v18, v18
	ds_read_u16 v19, v177
	ds_read_u16 v20, v177 offset:16384
	s_waitcnt lgkmcnt(1)
	v_lshlrev_b32_e32 v19, 16, v19
	s_waitcnt lgkmcnt(0)
	v_lshlrev_b32_e32 v20, 16, v20
	v_mul_f32_e32 v18, v18, v19
	v_cvt_pk_bf16_f32 v18, v18, s0
	ds_write_b16 v177, v18
	v_mul_f32_e32 v18, v21, v20
	v_cvt_pk_bf16_f32 v18, v18, s0
	ds_write_b16 v177, v18 offset:16384
	v_mul_f32_e32 v18, v16, v21
	v_mul_f32_e32 v18, v18, v20
	v_cvt_pk_bf16_f32 v18, v18, s0
	ds_write_b16 v178, v18 offset:32768
	v_add_f32_e32 v18, v33, v17
	v_mul_f32_e32 v18, 0x3fb8aa3b, v18
	v_exp_f32_e64 v21, -v18
	v_exp_f32_e32 v18, v18
	ds_read_u16 v19, v179
	ds_read_u16 v20, v179 offset:16384
	s_waitcnt lgkmcnt(1)
	v_lshlrev_b32_e32 v19, 16, v19
	s_waitcnt lgkmcnt(0)
	v_lshlrev_b32_e32 v20, 16, v20
	v_mul_f32_e32 v18, v18, v19
	v_cvt_pk_bf16_f32 v18, v18, s0
	ds_write_b16 v179, v18
	v_mul_f32_e32 v18, v21, v20
	v_cvt_pk_bf16_f32 v18, v18, s0
	ds_write_b16 v179, v18 offset:16384
	v_mul_f32_e32 v18, v16, v21
	v_mul_f32_e32 v18, v18, v20
	v_cvt_pk_bf16_f32 v18, v18, s0
	ds_write_b16 v180, v18 offset:32768
	v_add_f32_e32 v18, v34, v17
	v_mul_f32_e32 v18, 0x3fb8aa3b, v18
	v_exp_f32_e64 v21, -v18
	v_exp_f32_e32 v18, v18
	ds_read_u16 v19, v181
	ds_read_u16 v20, v181 offset:16384
	v_add_f32_e32 v17, v35, v17
	v_mul_f32_e32 v17, 0x3fb8aa3b, v17
	s_waitcnt lgkmcnt(1)
	v_lshlrev_b32_e32 v19, 16, v19
	s_waitcnt lgkmcnt(0)
	v_lshlrev_b32_e32 v20, 16, v20
	v_exp_f32_e32 v17, v17
	v_mul_f32_e32 v18, v18, v19
	v_cvt_pk_bf16_f32 v18, v18, s0
	ds_write_b16 v181, v18
	v_mul_f32_e32 v18, v21, v20
	v_cvt_pk_bf16_f32 v18, v18, s0
	ds_write_b16 v181, v18 offset:16384
	v_mul_f32_e32 v18, v16, v21
	v_mul_f32_e32 v18, v18, v20
	v_div_scale_f32 v20, s[2:3], v17, v17, 1.0
	v_rcp_f32_e32 v21, v20
	v_cvt_pk_bf16_f32 v18, v18, s0
	ds_write_b16 v182, v18 offset:32768
	ds_read_u16 v18, v183
	ds_read_u16 v19, v183 offset:16384
	v_fma_f32 v22, -v20, v21, 1.0
	v_fmac_f32_e32 v21, v22, v21
	v_div_scale_f32 v22, vcc, 1.0, v17, 1.0
	v_mul_f32_e32 v23, v22, v21
	v_fma_f32 v24, -v20, v23, v22
	v_fmac_f32_e32 v23, v24, v21
	v_fma_f32 v20, -v20, v23, v22
	s_waitcnt lgkmcnt(1)
	v_lshlrev_b32_e32 v18, 16, v18
	v_div_fmas_f32 v20, v20, v21, v23
	v_div_fixup_f32 v20, v20, v17, 1.0
	v_mul_f32_e32 v17, v17, v18
	s_waitcnt lgkmcnt(0)
	v_lshlrev_b32_e32 v19, 16, v19
	v_cvt_pk_bf16_f32 v17, v17, s0
	v_mul_f32_e32 v16, v16, v20
	ds_write_b16 v183, v17
	v_mul_f32_e32 v17, v20, v19
	v_mul_f32_e32 v16, v16, v19
	v_cvt_pk_bf16_f32 v17, v17, s0
	v_cvt_pk_bf16_f32 v16, v16, s0
	ds_write_b16 v183, v17 offset:16384
	ds_write_b16 v184, v16 offset:32768
	s_waitcnt lgkmcnt(0)
	s_barrier
	s_and_saveexec_b64 s[2:3], s[8:9]
	s_cbranch_execz .LBB0_396
; DEVI int crow(int r, int hi) { return (r & 3) + 8 * (r >> 2) + 4 * hi; }
; DEVI void gla_seq(const Params& p, int l, int item, char* lds) {
;     ...
;     if (wid < 4) {
;       f32x16 p0, p1, o;
; #pragma unroll
;       for (int r = 0; r < 16; ++r) { p0[r] = 0.f; p1[r] = 0.f; o[r] = 0.f; }
;       const int irow = iblk * 32 + r32;
; #pragma unroll
;       for (int d0 = 0; d0 < 8; ++d0) {
;         const int chn = d0 * 2 + hi;
;         const bf16x8 b0 = *(const bf16x8*)(ks + r32 * 256 + ((chn ^ (r32 & 7)) << 4));
;         const bf16x8 b1 = *(const bf16x8*)(ks + (32 + r32) * 256 + ((chn ^ (r32 & 7)) << 4));
;         const bf16x8 qf = *(const bf16x8*)(qs + irow * 256 + ((chn ^ (irow & 7)) << 4));
;         p0 = __builtin_amdgcn_mfma_f32_32x32x16_bf16(b0, qf, p0, 0, 0, 0);
;         p1 = __builtin_amdgcn_mfma_f32_32x32x16_bf16(b1, qf, p1, 0, 0, 0);
;       }
; #pragma unroll
;       for (int r = 0; r < 16; ++r) {
;         const int j0 = crow(r, hi), j1 = 32 + j0;
;         const bool k0 = dir ? (j0 < irow) : (j0 <= irow), k1 = dir ? (j1 < irow) : (j1 <= irow);
;         p0[r] = k0 ? p0[r] : 0.f; p1[r] = k1 ? p1[r] : 0.f;
;       }
;       bf16x8 pa0, pa1, pa2, pa3;
;       PK4(p0, 0, pa0); PK4(p0, 8, pa1); PK4(p1, 0, pa2); PK4(p1, 8, pa3);
;       const char* vrow = vT + (eblk * 32 + r32) * 144 + hi * 16;
;       o = __builtin_amdgcn_mfma_f32_32x32x16_bf16(pa0, *(const bf16x8*)(vrow), o, 0, 0, 0);
;       o = __builtin_amdgcn_mfma_f32_32x32x16_bf16(pa1, *(const bf16x8*)(vrow + 32), o, 0, 0, 0);
;       o = __builtin_amdgcn_mfma_f32_32x32x16_bf16(pa2, *(const bf16x8*)(vrow + 64), o, 0, 0, 0);
;       o = __builtin_amdgcn_mfma_f32_32x32x16_bf16(pa3, *(const bf16x8*)(vrow + 96), o, 0, 0, 0);
	v_add_u32_e32 v32, v137, v139
	ds_read_b128 v[16:19], v32 offset:16384
	v_add_u32_e32 v20, v138, v139
	ds_read_b128 v[68:71], v20
	v_add_u32_e32 v80, v137, v140
	ds_read_b128 v[76:79], v80 offset:16384
	ds_read_b128 v[32:35], v32 offset:24576
	v_add_u32_e32 v72, v138, v140
	ds_read_b128 v[72:75], v72
	v_add_u32_e32 v84, v137, v141
	s_waitcnt lgkmcnt(3)
	v_mfma_f32_32x32x16_bf16 v[16:31], v[16:19], v[68:71], 0
	v_add_u32_e32 v88, v137, v142
	v_add_u32_e32 v92, v137, v143
	v_add_u32_e32 v96, v137, v144
	v_add_u32_e32 v188, v137, v145
	v_add_u32_e32 v194, v137, v146
	v_readlane_b32 s68, v254, 30
	v_readlane_b32 s69, v254, 31
	s_waitcnt lgkmcnt(0)
	v_mfma_f32_32x32x16_bf16 v[16:31], v[76:79], v[72:75], v[16:31]
	ds_read_b128 v[76:79], v80 offset:24576
	ds_read_b128 v[80:83], v84 offset:16384
	s_add_i32 s27, s93, 0xffffff00
	s_cmp_lt_u32 s46, 4
	s_cselect_b32 s27, s93, s27
	s_cselect_b32 s29, 0x2000, 0
	v_mfma_f32_32x32x16_bf16 v[32:47], v[32:35], v[68:71], 0
	s_waitcnt lgkmcnt(1)
	v_mfma_f32_32x32x16_bf16 v[32:47], v[76:79], v[72:75], v[32:47]
	v_add_u32_e32 v76, v138, v141
	ds_read_b128 v[76:79], v76
	s_waitcnt lgkmcnt(0)
	v_mfma_f32_32x32x16_bf16 v[16:31], v[80:83], v[76:79], v[16:31]
	ds_read_b128 v[80:83], v84 offset:24576
	ds_read_b128 v[84:87], v88 offset:16384
	s_waitcnt lgkmcnt(1)
	v_mfma_f32_32x32x16_bf16 v[32:47], v[80:83], v[76:79], v[32:47]
	v_add_u32_e32 v80, v138, v142
	ds_read_b128 v[80:83], v80
	s_waitcnt lgkmcnt(0)
	v_mfma_f32_32x32x16_bf16 v[16:31], v[84:87], v[80:83], v[16:31]
	ds_read_b128 v[84:87], v88 offset:24576
	ds_read_b128 v[88:91], v92 offset:16384
	s_waitcnt lgkmcnt(1)
	v_mfma_f32_32x32x16_bf16 v[32:47], v[84:87], v[80:83], v[32:47]
	v_add_u32_e32 v84, v138, v143
	ds_read_b128 v[84:87], v84
	s_waitcnt lgkmcnt(0)
	v_mfma_f32_32x32x16_bf16 v[16:31], v[88:91], v[84:87], v[16:31]
	ds_read_b128 v[88:91], v92 offset:24576
	ds_read_b128 v[92:95], v96 offset:16384
	s_waitcnt lgkmcnt(1)
	v_mfma_f32_32x32x16_bf16 v[32:47], v[88:91], v[84:87], v[32:47]
	v_add_u32_e32 v88, v138, v144
	ds_read_b128 v[88:91], v88
	s_waitcnt lgkmcnt(0)
	v_mfma_f32_32x32x16_bf16 v[16:31], v[92:95], v[88:91], v[16:31]
	ds_read_b128 v[92:95], v96 offset:24576
	ds_read_b128 v[96:99], v188 offset:16384
	s_waitcnt lgkmcnt(1)
	v_mfma_f32_32x32x16_bf16 v[32:47], v[92:95], v[88:91], v[32:47]
	v_add_u32_e32 v92, v138, v145
	ds_read_b128 v[92:95], v92
	s_waitcnt lgkmcnt(0)
	v_mfma_f32_32x32x16_bf16 v[16:31], v[96:99], v[92:95], v[16:31]
	ds_read_b128 v[96:99], v188 offset:24576
	ds_read_b128 v[188:191], v194 offset:16384
	s_waitcnt lgkmcnt(1)
	v_mfma_f32_32x32x16_bf16 v[32:47], v[96:99], v[92:95], v[32:47]
	v_add_u32_e32 v96, v138, v146
	ds_read_b128 v[96:99], v96
	s_waitcnt lgkmcnt(0)
	v_mfma_f32_32x32x16_bf16 v[16:31], v[188:191], v[96:99], v[16:31]
	ds_read_b128 v[188:191], v194 offset:24576
	s_waitcnt lgkmcnt(0)
	v_mfma_f32_32x32x16_bf16 v[32:47], v[188:191], v[96:99], v[32:47]
	s_nop 8
	v_cndmask_b32_e64 v16, 0, v16, s[72:73]
	v_cndmask_b32_e64 v27, 0, v27, s[50:51]
	v_cndmask_b32_e64 v28, 0, v28, s[38:39]
	v_cndmask_b32_e64 v29, 0, v29, s[42:43]
	v_cndmask_b32_e64 v30, 0, v30, s[76:77]
	v_cndmask_b32_e64 v31, 0, v31, s[80:81]
	v_cndmask_b32_e64 v188, 0, v32, s[68:69]
	v_readlane_b32 s68, v254, 32
	v_readlane_b32 s69, v254, 33
	v_cndmask_b32_e64 v199, 0, v42, s[48:49]
	v_cndmask_b32_e64 v200, 0, v43, s[30:31]
	v_cndmask_b32_e64 v17, 0, v17, s[68:69]
	v_readlane_b32 s68, v254, 34
	v_readlane_b32 s69, v254, 35
	v_cvt_pk_bf16_f32 v16, v16, v17
	v_cndmask_b32_e64 v44, 0, v44, s[40:41]
	v_cndmask_b32_e64 v189, 0, v33, s[68:69]
	v_readlane_b32 s68, v254, 36
	v_readlane_b32 s69, v254, 37
	v_cndmask_b32_e64 v45, 0, v45, s[44:45]
	v_cndmask_b32_e64 v46, 0, v46, s[78:79]
	v_cndmask_b32_e64 v18, 0, v18, s[68:69]
	v_readlane_b32 s68, v254, 38
	v_readlane_b32 s69, v254, 39
	v_cndmask_b32_e64 v47, 0, v47, s[82:83]
	s_nop 0
	v_cndmask_b32_e64 v190, 0, v34, s[68:69]
	v_readlane_b32 s68, v254, 40
	v_readlane_b32 s69, v254, 41
	v_cvt_pk_bf16_f32 v34, v28, v29
	s_nop 0
	v_cndmask_b32_e64 v19, 0, v19, s[68:69]
	v_readlane_b32 s68, v254, 42
	v_readlane_b32 s69, v254, 43
	v_cvt_pk_bf16_f32 v17, v18, v19
	s_nop 0
	v_cndmask_b32_e64 v191, 0, v35, s[68:69]
	v_readlane_b32 s68, v254, 44
	v_readlane_b32 s69, v254, 45
	v_cvt_pk_bf16_f32 v35, v30, v31
	s_nop 0
	v_cndmask_b32_e64 v20, 0, v20, s[68:69]
	v_readlane_b32 s68, v254, 46
	v_readlane_b32 s69, v254, 47
	s_nop 1
	v_cndmask_b32_e64 v194, 0, v36, s[68:69]
	v_readlane_b32 s68, v254, 48
	v_readlane_b32 s69, v254, 49
	v_cvt_pk_bf16_f32 v36, v188, v189
	s_nop 0
	v_cndmask_b32_e64 v21, 0, v21, s[68:69]
	v_readlane_b32 s68, v254, 50
	v_readlane_b32 s69, v254, 51
	v_cvt_pk_bf16_f32 v18, v20, v21
	s_nop 1
	v_permlane32_swap_b32_e32 v16, v18
	v_cndmask_b32_e64 v195, 0, v37, s[68:69]
	v_readlane_b32 s68, v254, 52
	v_readlane_b32 s69, v254, 53
	v_cvt_pk_bf16_f32 v37, v190, v191
	s_nop 0
	v_cndmask_b32_e64 v22, 0, v22, s[68:69]
	v_readlane_b32 s68, v254, 54
	v_readlane_b32 s69, v254, 55
	s_nop 1
	v_cndmask_b32_e64 v196, 0, v38, s[68:69]
	v_readlane_b32 s68, v254, 56
	v_readlane_b32 s69, v254, 57
	v_cvt_pk_bf16_f32 v38, v194, v195
	s_nop 1
	v_permlane32_swap_b32_e32 v36, v38
	v_cndmask_b32_e64 v23, 0, v23, s[68:69]
	v_readlane_b32 s68, v254, 58
	v_readlane_b32 s69, v254, 59
	v_cvt_pk_bf16_f32 v19, v22, v23
	s_nop 1
	v_permlane32_swap_b32_e32 v17, v19
	v_cndmask_b32_e64 v39, 0, v39, s[68:69]
	v_readlane_b32 s68, v254, 60
	v_readlane_b32 s69, v254, 61
	ds_read_b128 v[20:23], v187 offset:51200
	v_cvt_pk_bf16_f32 v39, v196, v39
	v_cndmask_b32_e64 v24, 0, v24, s[68:69]
	v_readlane_b32 s68, v254, 62
	v_readlane_b32 s69, v254, 63
	v_permlane32_swap_b32_e32 v37, v39
	s_nop 0
	v_cndmask_b32_e64 v197, 0, v40, s[68:69]
	v_readlane_b32 s68, v255, 0
	v_readlane_b32 s69, v255, 1
	s_nop 1
	v_cndmask_b32_e64 v25, 0, v25, s[68:69]
	v_readlane_b32 s68, v255, 2
	v_readlane_b32 s69, v255, 3
	v_cvt_pk_bf16_f32 v32, v24, v25
	s_nop 1
	v_permlane32_swap_b32_e32 v32, v34
	v_cndmask_b32_e64 v198, 0, v41, s[68:69]
	v_readlane_b32 s68, v255, 4
	v_readlane_b32 s69, v255, 5
	ds_read_b128 v[40:43], v187 offset:51232
	s_nop 0
	v_cndmask_b32_e64 v26, 0, v26, s[68:69]
	v_cvt_pk_bf16_f32 v33, v26, v27
	s_waitcnt lgkmcnt(1)
; DEVI u16 f2bf(float f) { return (u16)(cvtpk(f, 0.f) & 0xffffu); }
; DEVI int crow(int r, int hi) { return (r & 3) + 8 * (r >> 2) + 4 * hi; }
; DEVI void gla_seq(const Params& p, int l, int item, char* lds) {
;     ...
;       o = __builtin_amdgcn_mfma_f32_32x32x16_bf16(pa0, *(const bf16x8*)(vrow), o, 0, 0, 0);
;       o = __builtin_amdgcn_mfma_f32_32x32x16_bf16(pa1, *(const bf16x8*)(vrow + 32), o, 0, 0, 0);
;       o = __builtin_amdgcn_mfma_f32_32x32x16_bf16(pa2, *(const bf16x8*)(vrow + 64), o, 0, 0, 0);
;       o = __builtin_amdgcn_mfma_f32_32x32x16_bf16(pa3, *(const bf16x8*)(vrow + 96), o, 0, 0, 0);
;       const int erow = eblk * 32 + r32;
; #pragma unroll
;       for (int d0 = 0; d0 < 8; ++d0) {
;         const int chn = d0 * 2 + hi;
;         const bf16x8 qf = *(const bf16x8*)(qs + irow * 256 + ((chn ^ (irow & 7)) << 4));
;         const bf16x8 sf = *(const bf16x8*)(sTc + erow * 256 + ((chn ^ (erow & 7)) << 4));
;         o = __builtin_amdgcn_mfma_f32_32x32x16_bf16(qf, sf, o, 0, 0, 0);
;       }
; #pragma unroll
;       for (int r = 0; r < 16; ++r)
;         og[gla_row(bi, dir, cc, iblk * 32 + crow(r, hi)) * 1024 + h * 256 + sl * 64 + eblk * 32 + r32] = f2bf(o[r]);
	v_mfma_f32_32x32x16_bf16 v[16:31], v[16:19], v[20:23], 0
	v_permlane32_swap_b32_e32 v33, v35
	v_readlane_b32 s68, v253, 21
	s_waitcnt lgkmcnt(0)
	v_mfma_f32_32x32x16_bf16 v[16:31], v[32:35], v[40:43], v[16:31]
	ds_read_b128 v[40:43], v187 offset:51264
	v_cvt_pk_bf16_f32 v32, v197, v198
	v_cvt_pk_bf16_f32 v33, v199, v200
	v_cvt_pk_bf16_f32 v34, v44, v45
	v_cvt_pk_bf16_f32 v35, v46, v47
	s_nop 0
	v_permlane32_swap_b32_e32 v32, v34
	s_waitcnt lgkmcnt(0)
	v_mfma_f32_32x32x16_bf16 v[16:31], v[36:39], v[40:43], v[16:31]
	v_permlane32_swap_b32_e32 v33, v35
	ds_read_b128 v[36:39], v187 offset:51296
	s_waitcnt lgkmcnt(0)
	v_mfma_f32_32x32x16_bf16 v[16:31], v[32:35], v[36:39], v[16:31]
	v_lshl_add_u32 v36, s75, 14, v134
	v_add_u32_e32 v32, v36, v139
	ds_read_b128 v[32:35], v32 offset:60416
	s_waitcnt lgkmcnt(0)
	v_mfma_f32_32x32x16_bf16 v[16:31], v[68:71], v[32:35], v[16:31]
	v_add_u32_e32 v32, v36, v140
	ds_read_b128 v[32:35], v32 offset:60416
	s_waitcnt lgkmcnt(0)
	v_mfma_f32_32x32x16_bf16 v[16:31], v[72:75], v[32:35], v[16:31]
	v_add_u32_e32 v32, v36, v141
	ds_read_b128 v[32:35], v32 offset:60416
	s_waitcnt lgkmcnt(0)
	v_mfma_f32_32x32x16_bf16 v[16:31], v[76:79], v[32:35], v[16:31]
	v_add_u32_e32 v32, v36, v142
	ds_read_b128 v[32:35], v32 offset:60416
	s_waitcnt lgkmcnt(0)
	v_mfma_f32_32x32x16_bf16 v[16:31], v[80:83], v[32:35], v[16:31]
	v_add_u32_e32 v32, v36, v143
	ds_read_b128 v[32:35], v32 offset:60416
	s_waitcnt lgkmcnt(0)
	v_mfma_f32_32x32x16_bf16 v[16:31], v[84:87], v[32:35], v[16:31]
	v_add_u32_e32 v32, v36, v144
	ds_read_b128 v[32:35], v32 offset:60416
	s_waitcnt lgkmcnt(0)
	v_mfma_f32_32x32x16_bf16 v[16:31], v[88:91], v[32:35], v[16:31]
	v_add_u32_e32 v32, v36, v145
	ds_read_b128 v[32:35], v32 offset:60416
	v_add_u32_e32 v36, v36, v146
	ds_read_b128 v[36:39], v36 offset:60416
	s_waitcnt lgkmcnt(1)
	v_mfma_f32_32x32x16_bf16 v[16:31], v[92:95], v[32:35], v[16:31]
	v_or_b32_e32 v34, s27, v151
	s_cselect_b32 s27, 0xff, s61
	v_sub_u32_e32 v32, s27, v34
	s_add_i32 s29, s29, s68
	v_cndmask_b32_e64 v32, v32, v34, s[4:5]
	v_add_u32_e32 v32, s29, v32
	v_ashrrev_i32_e32 v33, 31, v32
	s_waitcnt lgkmcnt(0)
; DEVI u16 f2bf(float f) { return (u16)(cvtpk(f, 0.f) & 0xffffu); }
; DEVI int crow(int r, int hi) { return (r & 3) + 8 * (r >> 2) + 4 * hi; }
; DEVI long gla_row(int bi, int dir, int cc, int i) {
;   const int L = (cc < 4) ? CTXL : SEQ, c = (cc < 4) ? cc : cc - 4, rb = bi * ROWS + ((cc < 4) ? SEQ : 0);
;   const int tl = c * 64 + i;
;   return (long)(rb + (dir ? (L - 1 - tl) : tl));
; }
; DEVI void gla_seq(const Params& p, int l, int item, char* lds) {
;     ...
; #pragma unroll
;       for (int r = 0; r < 16; ++r)
;         og[gla_row(bi, dir, cc, iblk * 32 + crow(r, hi)) * 1024 + h * 256 + sl * 64 + eblk * 32 + r32] = f2bf(o[r]);
	v_mfma_f32_32x32x16_bf16 v[16:31], v[96:99], v[36:39], v[16:31]
	v_lshlrev_b64 v[32:33], 11, v[32:33]
	v_lshl_add_u64 v[32:33], v[102:103], 0, v[32:33]
	s_nop 9
	v_cvt_pk_bf16_f32 v16, v16, s0
	global_store_short v[32:33], v16, off
	v_or_b32_e32 v16, 1, v34
	v_cvt_pk_bf16_f32 v32, v17, s0
	v_sub_u32_e32 v17, s27, v16
	v_cndmask_b32_e64 v16, v17, v16, s[4:5]
	v_add_u32_e32 v16, s29, v16
	v_ashrrev_i32_e32 v17, 31, v16
	v_lshlrev_b64 v[16:17], 11, v[16:17]
	v_lshl_add_u64 v[16:17], v[102:103], 0, v[16:17]
	global_store_short v[16:17], v32, off
	v_or_b32_e32 v16, 2, v34
	v_sub_u32_e32 v17, s27, v16
	v_cndmask_b32_e64 v16, v17, v16, s[4:5]
	v_add_u32_e32 v16, s29, v16
	v_ashrrev_i32_e32 v17, 31, v16
	v_lshlrev_b64 v[16:17], 11, v[16:17]
	v_cvt_pk_bf16_f32 v18, v18, s0
	v_lshl_add_u64 v[16:17], v[102:103], 0, v[16:17]
	global_store_short v[16:17], v18, off
	v_or_b32_e32 v16, 3, v34
	v_sub_u32_e32 v17, s27, v16
	v_cndmask_b32_e64 v16, v17, v16, s[4:5]
	v_add_u32_e32 v16, s29, v16
	v_ashrrev_i32_e32 v17, 31, v16
	v_lshlrev_b64 v[16:17], 11, v[16:17]
	v_cvt_pk_bf16_f32 v18, v19, s0
	v_lshl_add_u64 v[16:17], v[102:103], 0, v[16:17]
	global_store_short v[16:17], v18, off
	v_or_b32_e32 v16, 8, v34
	v_sub_u32_e32 v17, s27, v16
	v_cndmask_b32_e64 v16, v17, v16, s[4:5]
	v_add_u32_e32 v16, s29, v16
	v_ashrrev_i32_e32 v17, 31, v16
	v_lshlrev_b64 v[16:17], 11, v[16:17]
	v_cvt_pk_bf16_f32 v18, v20, s0
	v_lshl_add_u64 v[16:17], v[102:103], 0, v[16:17]
	global_store_short v[16:17], v18, off
	v_or_b32_e32 v16, 9, v34
	v_sub_u32_e32 v17, s27, v16
	v_cndmask_b32_e64 v16, v17, v16, s[4:5]
	v_add_u32_e32 v16, s29, v16
	v_ashrrev_i32_e32 v17, 31, v16
	v_lshlrev_b64 v[16:17], 11, v[16:17]
	v_cvt_pk_bf16_f32 v18, v21, s0
	v_lshl_add_u64 v[16:17], v[102:103], 0, v[16:17]
	global_store_short v[16:17], v18, off
	v_or_b32_e32 v16, 10, v34
	v_sub_u32_e32 v17, s27, v16
	v_cndmask_b32_e64 v16, v17, v16, s[4:5]
	v_add_u32_e32 v16, s29, v16
	v_ashrrev_i32_e32 v17, 31, v16
	v_lshlrev_b64 v[16:17], 11, v[16:17]
	v_cvt_pk_bf16_f32 v18, v22, s0
	v_lshl_add_u64 v[16:17], v[102:103], 0, v[16:17]
	global_store_short v[16:17], v18, off
	v_or_b32_e32 v16, 11, v34
	v_sub_u32_e32 v17, s27, v16
	v_cndmask_b32_e64 v16, v17, v16, s[4:5]
	v_add_u32_e32 v16, s29, v16
	v_ashrrev_i32_e32 v17, 31, v16
	v_lshlrev_b64 v[16:17], 11, v[16:17]
	v_cvt_pk_bf16_f32 v18, v23, s0
	v_lshl_add_u64 v[16:17], v[102:103], 0, v[16:17]
	global_store_short v[16:17], v18, off
	v_or_b32_e32 v16, 16, v34
	v_sub_u32_e32 v17, s27, v16
	v_cndmask_b32_e64 v16, v17, v16, s[4:5]
	v_add_u32_e32 v16, s29, v16
	v_ashrrev_i32_e32 v17, 31, v16
	v_lshlrev_b64 v[16:17], 11, v[16:17]
	v_cvt_pk_bf16_f32 v18, v24, s0
	v_lshl_add_u64 v[16:17], v[102:103], 0, v[16:17]
	global_store_short v[16:17], v18, off
	v_or_b32_e32 v16, 17, v34
	v_sub_u32_e32 v17, s27, v16
	v_cndmask_b32_e64 v16, v17, v16, s[4:5]
	v_add_u32_e32 v16, s29, v16
	v_ashrrev_i32_e32 v17, 31, v16
	v_lshlrev_b64 v[16:17], 11, v[16:17]
	v_cvt_pk_bf16_f32 v18, v25, s0
	v_lshl_add_u64 v[16:17], v[102:103], 0, v[16:17]
	global_store_short v[16:17], v18, off
	v_or_b32_e32 v16, 18, v34
	v_sub_u32_e32 v17, s27, v16
	v_cndmask_b32_e64 v16, v17, v16, s[4:5]
	v_add_u32_e32 v16, s29, v16
	v_ashrrev_i32_e32 v17, 31, v16
	v_lshlrev_b64 v[16:17], 11, v[16:17]
	v_cvt_pk_bf16_f32 v18, v26, s0
	v_lshl_add_u64 v[16:17], v[102:103], 0, v[16:17]
	global_store_short v[16:17], v18, off
	v_or_b32_e32 v16, 19, v34
	v_sub_u32_e32 v17, s27, v16
	v_cndmask_b32_e64 v16, v17, v16, s[4:5]
	v_add_u32_e32 v16, s29, v16
	v_ashrrev_i32_e32 v17, 31, v16
	v_lshlrev_b64 v[16:17], 11, v[16:17]
	v_cvt_pk_bf16_f32 v18, v27, s0
	v_lshl_add_u64 v[16:17], v[102:103], 0, v[16:17]
	global_store_short v[16:17], v18, off
	v_or_b32_e32 v16, 24, v34
	v_sub_u32_e32 v17, s27, v16
	v_cndmask_b32_e64 v16, v17, v16, s[4:5]
	v_add_u32_e32 v16, s29, v16
	v_ashrrev_i32_e32 v17, 31, v16
	v_lshlrev_b64 v[16:17], 11, v[16:17]
	v_cvt_pk_bf16_f32 v18, v28, s0
	v_lshl_add_u64 v[16:17], v[102:103], 0, v[16:17]
	global_store_short v[16:17], v18, off
	v_or_b32_e32 v16, 25, v34
	v_sub_u32_e32 v17, s27, v16
	v_cndmask_b32_e64 v16, v17, v16, s[4:5]
	v_add_u32_e32 v16, s29, v16
	v_ashrrev_i32_e32 v17, 31, v16
	v_lshlrev_b64 v[16:17], 11, v[16:17]
	v_cvt_pk_bf16_f32 v18, v29, s0
	v_lshl_add_u64 v[16:17], v[102:103], 0, v[16:17]
	global_store_short v[16:17], v18, off
	v_or_b32_e32 v16, 26, v34
	v_sub_u32_e32 v17, s27, v16
	v_cndmask_b32_e64 v16, v17, v16, s[4:5]
	v_add_u32_e32 v16, s29, v16
	v_ashrrev_i32_e32 v17, 31, v16
	v_lshlrev_b64 v[16:17], 11, v[16:17]
	v_cvt_pk_bf16_f32 v18, v30, s0
	v_lshl_add_u64 v[16:17], v[102:103], 0, v[16:17]
	global_store_short v[16:17], v18, off
	v_or_b32_e32 v16, 27, v34
	v_sub_u32_e32 v17, s27, v16
	v_cndmask_b32_e64 v16, v17, v16, s[4:5]
	v_add_u32_e32 v16, s29, v16
	v_ashrrev_i32_e32 v17, 31, v16
	v_lshlrev_b64 v[16:17], 11, v[16:17]
	v_cvt_pk_bf16_f32 v18, v31, s0
	v_lshl_add_u64 v[16:17], v[102:103], 0, v[16:17]
	global_store_short v[16:17], v18, off
	s_branch .LBB0_396
